# itemwait with MIX1 item split 13:12 (scan workgroups take one more chunk-state item each than with 12:11)
# speedup vs baseline: 1.0006x; 1.0006x over previous
.LBB0_411:
	s_load_dwordx4 s[28:31], s[0:1], 0x78
	s_load_dwordx2 s[4:5], s[0:1], 0x90
	s_load_dwordx4 s[36:39], s[0:1], 0xa0
	s_mov_b64 s[6:7], -1
	s_and_b64 vcc, exec, s[42:43]
	s_cbranch_vccz .LBB0_413
	v_readlane_b32 s6, v254, 39
	v_readlane_b32 s7, v254, 40
	s_and_b64 s[6:7], s[6:7], exec
	s_movk_i32 s7, 0x322
	s_movk_i32 s6, 0x4c
	s_cselect_b32 s6, 0x42, s6
	s_cselect_b32 s7, s7, 0x318
	s_add_i32 s8, s7, s6
	s_mul_i32 s9, s94, 12
	s_add_i32 s8, s8, s9
	s_sub_i32 s9, s94, 64
	s_cmp_lt_u32 s9, s6
	s_mul_i32 s13, s9, 5
	s_cselect_b32 s12, 6, 5
	s_add_i32 s7, s13, s7
	s_min_u32 s6, s9, s6
	s_add_i32 s6, s7, s6
	s_add_i32 s7, s6, s12
	s_add_i32 s9, s8, 0xfffff8f4
	s_addk_i32 s8, 0xf900
	s_cmpk_lt_u32 s94, 0xd4
	s_cselect_b32 s34, s7, s8
	s_cselect_b32 s51, s6, s9
	s_mov_b64 s[6:7], 0
.LBB0_413:
	s_andn2_b64 vcc, exec, s[6:7]
	s_cbranch_vccnz .LBB0_415
	s_sub_i32 s6, s94, s60
	s_add_i32 s8, s6, 0x42
	s_and_b64 s[6:7], s[10:11], exec
	s_cselect_b32 s6, s94, s8
	s_mul_i32 s7, s6, 6
	s_mul_i32 s9, s6, 12
	s_mul_i32 s11, s6, 13
	s_add_i32 s8, s7, 6
	s_sub_i32 s10, s11, 43
	s_sub_i32 s11, s11, 56
	s_add_i32 s12, s9, 12
	s_cmp_lt_i32 s6, 8
	s_cselect_b32 s8, s8, s10
	s_cselect_b32 s10, s7, s11
	v_readlane_b32 s6, v254, 39
	v_readlane_b32 s7, v254, 40
	s_and_b64 s[6:7], s[6:7], exec
	s_cselect_b32 s34, s8, s12
	s_cselect_b32 s51, s10, s9
